# LN_in: gamma/beta preloaded once before the row loop; removes 16 per-chunk full memory waits per 4 rows
# speedup vs baseline: 1.0062x; 1.0062x over previous
; __device__ __forceinline__ void ln_rows4(const float* x, const float* g, const float* b, f16* h, unsigned char* h8, int m, int stride, int lane) {
;     f32x4 v[4][4];
; #pragma unroll
;     for (int r = 0; r < 4; ++r)
; #pragma unroll
;         for (int j = 0; j < 4; ++j) v[r][j] = ((const f32x4*)(x + (size_t)(m + r * stride) * DM))[lane + 64 * j];
;     asm volatile("" ::: "memory");
; #pragma unroll
;     for (int r = 0; r < 4; ++r) { float s = 0.f;
; #pragma unroll
;         for (int j = 0; j < 4; ++j) s += (v[r][j].x + v[r][j].y) + (v[r][j].z + v[r][j].w);
;         const float mean = wave_sum(s) * (1.f / DM); float s2 = 0.f;
; __global__ void __launch_bounds__(NTHREADS, 2) mk_fwd(Args args) {
;     ...
;             if (step == 0) { const float* src = args.in[0]; const float* g = args.in[2]; const float* b = args.in[3];
;                 int m = gw;
;                 for (; m + 3 * NGW < M; m += 4 * NGW) ln_rows4(src, g, b, H16, ws + WS_H8, m, NGW, lane);
.LBB0_572:
	v_readlane_b32 s4, v255, 3
	v_readlane_b32 s5, v255, 4
	s_andn2_b64 vcc, exec, s[4:5]
	s_cbranch_vccnz .LBB0_579
	s_add_i32 s4, s10, s87
	s_cmpk_gt_i32 s4, 0x3fff
	v_lshlrev_b32_e32 v32, 4, v71
	s_mov_b32 s6, s10
	s_cbranch_scc1 .LBB0_576
	v_readlane_b32 s4, v253, 4
	s_waitcnt lgkmcnt(0)
	v_lshlrev_b32_e32 v0, 3, v71
	v_mov_b32_e32 v1, v33
	v_readlane_b32 s5, v253, 5
	v_lshlrev_b32_e32 v2, 2, v71
	v_mov_b32_e32 v3, v33
	v_lshl_add_u64 v[68:69], s[4:5], 0, v[0:1]
	v_readlane_b32 s4, v252, 26
	v_readlane_b32 s5, v252, 27
	s_ashr_i32 s11, s10, 31
	v_readlane_b32 s16, v253, 52
	v_lshl_add_u64 v[72:73], s[4:5], 0, v[2:3]
	s_lshl_b64 s[4:5], s[10:11], 10
	v_or_b32_e32 v74, s4, v2
	v_mov_b32_e32 v75, s5
	s_lshl_b64 s[4:5], s[10:11], 11
	v_or_b32_e32 v76, s4, v0
	v_mov_b32_e32 v77, s5
	v_readlane_b32 s4, v253, 41
	v_readlane_b32 s5, v255, 5
	s_add_i32 s4, s4, s5
	s_ashr_i32 s5, s4, 31
	s_lshl_b64 s[6:7], s[4:5], 12
	v_readlane_b32 s17, v253, 53
	s_add_u32 s8, s16, s6
	s_addc_u32 s9, s17, s7
	s_lshl_b64 s[6:7], s[10:11], 12
	s_add_u32 s12, s16, s6
	v_readlane_b32 s18, v253, 54
	v_readlane_b32 s20, v253, 56
	v_readlane_b32 s21, v253, 57
	v_readlane_b32 s22, v253, 58
	v_readlane_b32 s23, v253, 59
	s_addc_u32 s13, s17, s7
	s_lshl_b64 s[6:7], s[4:5], 10
	s_lshl_b64 s[4:5], s[4:5], 11
	v_lshl_add_u64 v[62:63], s[20:21], 0, v[32:33]
	v_lshl_add_u64 v[64:65], s[22:23], 0, v[32:33]
	v_lshl_add_u64 v[66:67], s[16:17], 0, v[32:33]
	v_or_b32_e32 v78, s6, v2
	v_mov_b32_e32 v79, s7
	v_or_b32_e32 v80, s4, v0
	v_mov_b32_e32 v81, s5
	s_mov_b32 s6, s10
	s_mov_b32 s7, 0xf800000
	s_mov_b32 s11, 0x2400000
	s_mov_b32 s18, 0x13400000
	v_readlane_b32 s19, v253, 55
	v_readlane_b32 s24, v253, 60
	v_readlane_b32 s25, v253, 61
	v_readlane_b32 s26, v253, 62
	v_readlane_b32 s27, v253, 63
	v_readlane_b32 s28, v254, 0
	v_readlane_b32 s29, v254, 1
	v_readlane_b32 s30, v254, 2
	v_readlane_b32 s31, v254, 3
	global_load_dwordx4 v[96:99], v[62:63], off
	global_load_dwordx4 v[112:115], v[64:65], off
	global_load_dwordx4 v[100:103], v[62:63], off offset:1024
	global_load_dwordx4 v[116:119], v[64:65], off offset:1024
	global_load_dwordx4 v[104:107], v[62:63], off offset:2048
	global_load_dwordx4 v[120:123], v[64:65], off offset:2048
	global_load_dwordx4 v[108:111], v[62:63], off offset:3072
	global_load_dwordx4 v[124:127], v[64:65], off offset:3072
.LBB0_575:
	v_lshl_add_u64 v[0:1], s[12:13], 0, v[32:33]
	global_load_dwordx4 v[82:85], v[0:1], off
	global_load_dwordx4 v[58:61], v[0:1], off offset:1024
	global_load_dwordx4 v[54:57], v[0:1], off offset:2048
	global_load_dwordx4 v[50:53], v[0:1], off offset:3072
	s_add_i32 s16, s45, s6
	s_ashr_i32 s17, s16, 31
	s_add_i32 s14, s87, s6
	v_lshl_add_u64 v[0:1], s[8:9], 0, v[32:33]
	s_lshl_b64 s[4:5], s[16:17], 12
	s_ashr_i32 s15, s14, 31
	global_load_dwordx4 v[46:49], v[0:1], off
	global_load_dwordx4 v[42:45], v[0:1], off offset:1024
	global_load_dwordx4 v[38:41], v[0:1], off offset:2048
	global_load_dwordx4 v[34:37], v[0:1], off offset:3072
	v_lshl_add_u64 v[0:1], v[66:67], 0, s[4:5]
	s_lshl_b64 s[4:5], s[14:15], 12
	global_load_dwordx4 v[28:31], v[0:1], off
	global_load_dwordx4 v[24:27], v[0:1], off offset:1024
	global_load_dwordx4 v[20:23], v[0:1], off offset:2048
	global_load_dwordx4 v[16:19], v[0:1], off offset:3072
	v_lshl_add_u64 v[0:1], v[66:67], 0, s[4:5]
	global_load_dwordx4 v[12:15], v[0:1], off
	global_load_dwordx4 v[8:11], v[0:1], off offset:1024
	global_load_dwordx4 v[4:7], v[0:1], off offset:2048
	s_nop 0
	global_load_dwordx4 v[0:3], v[0:1], off offset:3072
	s_add_i32 s6, s6, s36
	s_waitcnt vmcnt(0)
	v_mov_b32_e32 v86, v83
	v_mov_b32_e32 v87, v84
	v_mov_b32_e32 v88, v82
	v_mov_b32_e32 v89, v85
	v_pk_add_f32 v[86:87], v[86:87], v[88:89]
	v_mov_b32_e32 v88, v59
	v_mov_b32_e32 v89, v60
	v_mov_b32_e32 v90, v58
	v_mov_b32_e32 v91, v61
	v_pk_add_f32 v[88:89], v[88:89], v[90:91]
	v_add_f32_e32 v86, v86, v87
	v_pk_add_f32 v[88:89], v[88:89], v[88:89] op_sel:[0,1] op_sel_hi:[1,0]
	v_add_f32_e32 v86, 0, v86
	v_add_f32_e32 v90, v54, v55
	v_add_f32_e32 v92, v56, v57
	v_mov_b32_e32 v87, v50
	v_mov_b32_e32 v89, v51
	v_mov_b32_e32 v91, v52
	v_mov_b32_e32 v93, v53
	v_pk_add_f32 v[86:87], v[86:87], v[88:89]
	v_pk_add_f32 v[88:89], v[90:91], v[92:93]
	s_nop 0
	v_pk_add_f32 v[86:87], v[86:87], v[88:89]
	s_nop 0
	v_add_f32_e32 v86, v86, v87
	v_mbcnt_lo_u32_b32 v87, -1, 0
	v_mbcnt_hi_u32_b32 v87, -1, v87
	s_nop 0
	v_lshlrev_b32_e32 v87, 2, v87
	v_xor_b32_e32 v87, 4, v87
	ds_bpermute_b32 v87, v87, v86
	s_waitcnt lgkmcnt(0)
	v_add_f32_e32 v86, v86, v87
	v_mbcnt_lo_u32_b32 v87, -1, 0
	v_mbcnt_hi_u32_b32 v87, -1, v87
	s_nop 0
	v_lshlrev_b32_e32 v87, 2, v87
	v_xor_b32_e32 v87, 8, v87
	ds_bpermute_b32 v87, v87, v86
	s_waitcnt lgkmcnt(0)
	v_add_f32_e32 v86, v86, v87
	v_mbcnt_lo_u32_b32 v87, -1, 0
	v_mbcnt_hi_u32_b32 v87, -1, v87
	s_nop 0
	v_lshlrev_b32_e32 v87, 2, v87
	v_xor_b32_e32 v87, 16, v87
	ds_bpermute_b32 v87, v87, v86
	s_waitcnt lgkmcnt(0)
	v_add_f32_e32 v86, v86, v87
	v_mbcnt_lo_u32_b32 v87, -1, 0
	v_mbcnt_hi_u32_b32 v87, -1, v87
	s_nop 0
	v_lshlrev_b32_e32 v87, 2, v87
	v_xor_b32_e32 v87, 32, v87
	ds_bpermute_b32 v87, v87, v86
	s_waitcnt lgkmcnt(0)
	v_add_f32_e32 v86, v86, v87
	v_mbcnt_lo_u32_b32 v87, -1, 0
	v_mbcnt_hi_u32_b32 v87, -1, v87
	s_nop 0
	v_lshlrev_b32_e32 v87, 2, v87
	v_xor_b32_e32 v87, 64, v87
	ds_bpermute_b32 v87, v87, v86
	s_waitcnt lgkmcnt(0)
	v_add_f32_e32 v86, v86, v87
	v_mbcnt_lo_u32_b32 v87, -1, 0
	v_mbcnt_hi_u32_b32 v87, -1, v87
	s_nop 0
	v_lshlrev_b32_e32 v87, 2, v87
	v_xor_b32_e32 v87, 0x80, v87
	ds_bpermute_b32 v87, v87, v86
	s_waitcnt lgkmcnt(0)
; __device__ __forceinline__ unsigned pk4_fp8(float a, float b, float c, float d) { int w = __builtin_amdgcn_cvt_pk_fp8_f32(a, b, 0, false); w = __builtin_amdgcn_cvt_pk_fp8_f32(c, d, w, true); return (unsigned)w; }
; __device__ __forceinline__ void ln_rows4(const float* x, const float* g, const float* b, f16* h, unsigned char* h8, int m, int stride, int lane) {
;     ...
;         const float mean = wave_sum(s) * (1.f / DM); float s2 = 0.f;
; #pragma unroll
;         for (int j = 0; j < 4; ++j) { v[r][j] = v[r][j] - mean; s2 += (v[r][j].x * v[r][j].x + v[r][j].y * v[r][j].y) + (v[r][j].z * v[r][j].z + v[r][j].w * v[r][j].w); }
;         const float rstd = 1.f / sqrtf(wave_sum(s2) * (1.f / DM) + LN_EPS);
; #pragma unroll
;         for (int j = 0; j < 4; ++j) { const f32x4 gg = ((const f32x4*)g)[lane + 64 * j], bb = ((const f32x4*)b)[lane + 64 * j]; const f32x4 y = v[r][j] * rstd * gg + bb;
;             u32x2 w; w.x = rd<D_H>(pk_f16(y.x, y.y)); w.y = rd<D_H>(pk_f16(y.z, y.w)); ((u32x2*)(h + (size_t)(m + r * stride) * DM))[lane + 64 * j] = w;
;             ((unsigned*)(h8 + (size_t)(m + r * stride) * DM))[lane + 64 * j] = pk4_fp8(y.x, y.y, y.z, y.w); } }
	v_add_f32_e32 v92, v86, v87
	v_fmamk_f32 v95, v92, 0xba800000, v83
	v_fmamk_f32 v94, v92, 0xba800000, v82
	v_fmamk_f32 v85, v92, 0xba800000, v85
	v_fmac_f32_e32 v84, 0xba800000, v92
	v_pk_mul_f32 v[82:83], v[84:85], v[84:85]
	v_pk_mul_f32 v[86:87], v[94:95], v[94:95]
	v_fmamk_f32 v61, v92, 0xba800000, v61
	v_pk_mov_b32 v[88:89], v[86:87], v[82:83] op_sel:[1,0]
	v_mov_b32_e32 v87, v83
	v_pk_add_f32 v[82:83], v[88:89], v[86:87]
	v_fmac_f32_e32 v60, 0xba800000, v92
	v_pk_add_f32 v[86:87], v[82:83], v[82:83] op_sel_hi:[0,1]
	v_fmamk_f32 v83, v92, 0xba800000, v59
	v_fmamk_f32 v82, v92, 0xba800000, v58
	v_pk_mul_f32 v[58:59], v[60:61], v[60:61]
	v_pk_mul_f32 v[88:89], v[82:83], v[82:83]
	v_fmac_f32_e32 v56, 0xba800000, v92
	v_pk_mov_b32 v[90:91], v[88:89], v[58:59] op_sel:[1,0]
	v_mov_b32_e32 v89, v59
	v_pk_add_f32 v[58:59], v[90:91], v[88:89]
	v_fmamk_f32 v57, v92, 0xba800000, v57
	v_pk_add_f32 v[88:89], v[58:59], v[58:59] op_sel_hi:[0,1]
	v_fmamk_f32 v58, v92, 0xba800000, v54
	v_fmamk_f32 v59, v92, 0xba800000, v55
	v_mul_f32_e32 v54, v58, v58
	v_pk_fma_f32 v[54:55], v[58:59], v[58:59], v[54:55] op_sel_hi:[1,1,0]
	v_fmamk_f32 v53, v92, 0xba800000, v53
	v_mul_f32_e32 v54, v56, v56
	v_pk_fma_f32 v[90:91], v[56:57], v[56:57], v[54:55] op_sel_hi:[1,1,0]
	v_fmamk_f32 v52, v92, 0xba800000, v52
	v_fmamk_f32 v51, v92, 0xba800000, v51
	v_fmac_f32_e32 v50, 0xba800000, v92
	v_mul_f32_e32 v54, v50, v50
	v_mul_f32_e32 v90, v51, v51
	v_mul_f32_e32 v86, v52, v52
	v_mul_f32_e32 v88, v53, v53
	v_pk_add_f32 v[54:55], v[54:55], v[90:91]
	v_pk_add_f32 v[86:87], v[86:87], v[88:89]
	s_nop 0
	v_pk_add_f32 v[54:55], v[54:55], v[86:87]
	s_nop 0
	v_add_f32_e32 v54, v54, v55
	v_mbcnt_lo_u32_b32 v55, -1, 0
	v_mbcnt_hi_u32_b32 v55, -1, v55
	s_nop 0
	v_lshlrev_b32_e32 v55, 2, v55
	v_xor_b32_e32 v55, 4, v55
	ds_bpermute_b32 v55, v55, v54
	s_waitcnt lgkmcnt(0)
	v_add_f32_e32 v54, v54, v55
	v_mbcnt_lo_u32_b32 v55, -1, 0
	v_mbcnt_hi_u32_b32 v55, -1, v55
	s_nop 0
	v_lshlrev_b32_e32 v55, 2, v55
	v_xor_b32_e32 v55, 8, v55
	ds_bpermute_b32 v55, v55, v54
	s_waitcnt lgkmcnt(0)
	v_add_f32_e32 v54, v54, v55
	v_mbcnt_lo_u32_b32 v55, -1, 0
	v_mbcnt_hi_u32_b32 v55, -1, v55
	s_nop 0
	v_lshlrev_b32_e32 v55, 2, v55
	v_xor_b32_e32 v55, 16, v55
	ds_bpermute_b32 v55, v55, v54
	s_waitcnt lgkmcnt(0)
	v_add_f32_e32 v54, v54, v55
	v_mbcnt_lo_u32_b32 v55, -1, 0
	v_mbcnt_hi_u32_b32 v55, -1, v55
	s_nop 0
	v_lshlrev_b32_e32 v55, 2, v55
	v_xor_b32_e32 v55, 32, v55
	ds_bpermute_b32 v55, v55, v54
	s_waitcnt lgkmcnt(0)
	v_add_f32_e32 v54, v54, v55
	v_mbcnt_lo_u32_b32 v55, -1, 0
	v_mbcnt_hi_u32_b32 v55, -1, v55
	s_nop 0
	v_lshlrev_b32_e32 v55, 2, v55
	v_xor_b32_e32 v55, 64, v55
	ds_bpermute_b32 v55, v55, v54
	s_waitcnt lgkmcnt(0)
	v_add_f32_e32 v54, v54, v55
	v_mbcnt_lo_u32_b32 v55, -1, 0
	v_mbcnt_hi_u32_b32 v55, -1, v55
	s_nop 0
	v_lshlrev_b32_e32 v55, 2, v55
	v_xor_b32_e32 v55, 0x80, v55
	ds_bpermute_b32 v55, v55, v54
	s_waitcnt lgkmcnt(0)
	v_add_f32_e32 v54, v54, v55
	v_fmamk_f32 v54, v54, 0x3a800000, v223
	v_cmp_gt_f32_e32 vcc, s7, v54
	v_mul_f32_e32 v55, 0x4f800000, v54
	s_nop 0
	v_cndmask_b32_e32 v54, v54, v55, vcc
	v_sqrt_f32_e32 v55, v54
	s_nop 0
	v_add_u32_e32 v86, -1, v55
	v_fma_f32 v87, -v86, v55, v54
	v_cmp_ge_f32_e64 s[4:5], 0, v87
	v_add_u32_e32 v87, 1, v55
	s_nop 0
	v_cndmask_b32_e64 v86, v55, v86, s[4:5]
	v_fma_f32 v55, -v87, v55, v54
	v_cmp_lt_f32_e64 s[4:5], 0, v55
	s_nop 1
	v_cndmask_b32_e64 v55, v86, v87, s[4:5]
	v_mul_f32_e32 v86, 0x37800000, v55
	v_cndmask_b32_e32 v55, v55, v86, vcc
	v_cmp_class_f32_e32 vcc, v54, v224
	s_nop 1
	v_cndmask_b32_e32 v54, v55, v54, vcc
	v_div_scale_f32 v55, s[4:5], v54, v54, 1.0
	v_rcp_f32_e32 v86, v55
	s_nop 0
	v_fma_f32 v87, -v55, v86, 1.0
	v_fmac_f32_e32 v86, v87, v86
	v_div_scale_f32 v87, vcc, 1.0, v54, 1.0
	v_mul_f32_e32 v88, v87, v86
	v_fma_f32 v89, -v55, v88, v87
	v_fmac_f32_e32 v88, v89, v86
	v_fma_f32 v55, -v55, v88, v87
	v_div_fmas_f32 v55, v55, v86, v88
	v_div_fixup_f32 v54, v55, v54, 1.0
	v_pk_mul_f32 v[94:95], v[94:95], v[54:55] op_sel_hi:[1,0]
	v_pk_mul_f32 v[84:85], v[84:85], v[54:55] op_sel_hi:[1,0]
	v_pk_fma_f32 v[86:87], v[96:97], v[94:95], v[112:113]
	s_nop 0
	v_cvt_pk_f16_f32 v55, v86, v87
	v_pk_fma_f32 v[84:85], v[98:99], v[84:85], v[114:115]
	v_add_u32_e32 v55, 0x20002, v55
	v_and_b32_e32 v88, 0xfffcfffc, v55
	v_cvt_pk_f16_f32 v55, v84, v85
	v_add_u32_e32 v55, 0x20002, v55
	v_and_b32_e32 v89, 0xfffcfffc, v55
	v_mov_b32_e32 v55, v33
	v_cvt_pk_fp8_f32 v55, v86, v87
	v_lshl_add_u64 v[90:91], s[54:55], 0, v[76:77]
	v_add_co_u32_e32 v94, vcc, s11, v90
	v_cvt_pk_fp8_f32 v55, v84, v85 op_sel:[0,0,1]
	s_nop 0
	v_addc_co_u32_e32 v95, vcc, 0, v91, vcc
	v_lshl_add_u64 v[84:85], s[54:55], 0, v[74:75]
	v_add_co_u32_e32 v84, vcc, s18, v84
	global_store_dwordx2 v[94:95], v[88:89], off
	s_nop 0
	v_addc_co_u32_e32 v85, vcc, 0, v85, vcc
	global_store_dword v[84:85], v55, off
	v_pk_mul_f32 v[82:83], v[82:83], v[54:55] op_sel_hi:[1,0]
	v_pk_mul_f32 v[60:61], v[60:61], v[54:55] op_sel_hi:[1,0]
	v_lshl_add_u64 v[74:75], v[74:75], 0, s[80:81]
	v_lshl_add_u64 v[76:77], v[76:77], 0, s[74:75]
	v_pk_fma_f32 v[82:83], v[100:101], v[82:83], v[116:117]
	s_nop 0
	v_cvt_pk_f16_f32 v55, v82, v83
	v_pk_fma_f32 v[60:61], v[102:103], v[60:61], v[118:119]
	v_add_u32_e32 v55, 0x20002, v55
	v_and_b32_e32 v86, 0xfffcfffc, v55
	v_cvt_pk_f16_f32 v55, v60, v61
	v_add_u32_e32 v55, 0x20002, v55
	v_and_b32_e32 v87, 0xfffcfffc, v55
	v_mov_b32_e32 v55, v33
	v_cvt_pk_fp8_f32 v55, v82, v83
	global_store_dwordx2 v[94:95], v[86:87], off offset:512
	v_cvt_pk_fp8_f32 v55, v60, v61 op_sel:[0,0,1]
	global_store_dword v[84:85], v55, off offset:256
	v_pk_mul_f32 v[58:59], v[58:59], v[54:55] op_sel_hi:[1,0]
; __device__ __forceinline__ unsigned pk4_fp8(float a, float b, float c, float d) { int w = __builtin_amdgcn_cvt_pk_fp8_f32(a, b, 0, false); w = __builtin_amdgcn_cvt_pk_fp8_f32(c, d, w, true); return (unsigned)w; }
; __device__ __forceinline__ void ln_rows4(const float* x, const float* g, const float* b, f16* h, unsigned char* h8, int m, int stride, int lane) {
;     ...
;         const float mean = wave_sum(s) * (1.f / DM); float s2 = 0.f;
; #pragma unroll
;         for (int j = 0; j < 4; ++j) { v[r][j] = v[r][j] - mean; s2 += (v[r][j].x * v[r][j].x + v[r][j].y * v[r][j].y) + (v[r][j].z * v[r][j].z + v[r][j].w * v[r][j].w); }
;         const float rstd = 1.f / sqrtf(wave_sum(s2) * (1.f / DM) + LN_EPS);
; #pragma unroll
;         for (int j = 0; j < 4; ++j) { const f32x4 gg = ((const f32x4*)g)[lane + 64 * j], bb = ((const f32x4*)b)[lane + 64 * j]; const f32x4 y = v[r][j] * rstd * gg + bb;
;             u32x2 w; w.x = rd<D_H>(pk_f16(y.x, y.y)); w.y = rd<D_H>(pk_f16(y.z, y.w)); ((u32x2*)(h + (size_t)(m + r * stride) * DM))[lane + 64 * j] = w;
;             ((unsigned*)(h8 + (size_t)(m + r * stride) * DM))[lane + 64 * j] = pk4_fp8(y.x, y.y, y.z, y.w); } }
	v_pk_mul_f32 v[56:57], v[56:57], v[54:55] op_sel_hi:[1,0]
	v_pk_fma_f32 v[58:59], v[104:105], v[58:59], v[120:121]
	s_nop 0
	v_cvt_pk_f16_f32 v55, v58, v59
	v_pk_fma_f32 v[56:57], v[106:107], v[56:57], v[122:123]
	v_add_u32_e32 v55, 0x20002, v55
	v_and_b32_e32 v60, 0xfffcfffc, v55
	v_cvt_pk_f16_f32 v55, v56, v57
	v_add_u32_e32 v55, 0x20002, v55
	v_and_b32_e32 v61, 0xfffcfffc, v55
	v_mov_b32_e32 v55, v33
	v_cvt_pk_fp8_f32 v55, v58, v59
	global_store_dwordx2 v[94:95], v[60:61], off offset:1024
	v_cvt_pk_fp8_f32 v55, v56, v57 op_sel:[0,0,1]
	global_store_dword v[84:85], v55, off offset:512
	v_pk_mul_f32 v[50:51], v[50:51], v[54:55] op_sel_hi:[1,0]
	v_pk_mul_f32 v[52:53], v[52:53], v[54:55] op_sel_hi:[1,0]
	v_pk_fma_f32 v[50:51], v[50:51], v[108:109], v[124:125]
	v_pk_fma_f32 v[52:53], v[52:53], v[110:111], v[126:127]
	v_cvt_pk_f16_f32 v54, v50, v51
	v_cvt_pk_f16_f32 v55, v52, v53
	v_add_u32_e32 v54, 0x20002, v54
	v_add_u32_e32 v55, 0x20002, v55
	v_and_b32_e32 v54, 0xfffcfffc, v54
	v_and_b32_e32 v55, 0xfffcfffc, v55
	global_store_dwordx2 v[94:95], v[54:55], off offset:1536
	v_mov_b32_e32 v54, v33
	v_cvt_pk_fp8_f32 v54, v50, v51
	v_mov_b32_e32 v50, v47
	v_mov_b32_e32 v51, v48
	v_mov_b32_e32 v55, v45
	v_cvt_pk_fp8_f32 v54, v52, v53 op_sel:[0,0,1]
	v_mov_b32_e32 v52, v46
	v_mov_b32_e32 v53, v49
	v_pk_add_f32 v[50:51], v[50:51], v[52:53]
	global_store_dword v[84:85], v54, off offset:768
	v_mov_b32_e32 v52, v43
	v_mov_b32_e32 v53, v44
	v_mov_b32_e32 v54, v42
	v_pk_add_f32 v[52:53], v[52:53], v[54:55]
	v_add_f32_e32 v50, v50, v51
	v_pk_add_f32 v[52:53], v[52:53], v[52:53] op_sel:[0,1] op_sel_hi:[1,0]
	v_add_f32_e32 v50, 0, v50
	v_add_f32_e32 v54, v38, v39
	v_add_f32_e32 v56, v40, v41
	v_mov_b32_e32 v51, v34
	v_mov_b32_e32 v53, v35
	v_mov_b32_e32 v55, v36
	v_mov_b32_e32 v57, v37
	v_pk_add_f32 v[50:51], v[50:51], v[52:53]
	v_pk_add_f32 v[52:53], v[54:55], v[56:57]
	s_nop 0
	v_pk_add_f32 v[50:51], v[50:51], v[52:53]
	s_nop 0
	v_add_f32_e32 v50, v50, v51
	v_mbcnt_lo_u32_b32 v51, -1, 0
	v_mbcnt_hi_u32_b32 v51, -1, v51
	s_nop 0
	v_lshlrev_b32_e32 v51, 2, v51
	v_xor_b32_e32 v51, 4, v51
	ds_bpermute_b32 v51, v51, v50
	s_waitcnt lgkmcnt(0)
	v_add_f32_e32 v50, v50, v51
	v_mbcnt_lo_u32_b32 v51, -1, 0
	v_mbcnt_hi_u32_b32 v51, -1, v51
	s_nop 0
	v_lshlrev_b32_e32 v51, 2, v51
	v_xor_b32_e32 v51, 8, v51
	ds_bpermute_b32 v51, v51, v50
	s_waitcnt lgkmcnt(0)
	v_add_f32_e32 v50, v50, v51
	v_mbcnt_lo_u32_b32 v51, -1, 0
	v_mbcnt_hi_u32_b32 v51, -1, v51
	s_nop 0
	v_lshlrev_b32_e32 v51, 2, v51
	v_xor_b32_e32 v51, 16, v51
	ds_bpermute_b32 v51, v51, v50
	s_waitcnt lgkmcnt(0)
	v_add_f32_e32 v50, v50, v51
	v_mbcnt_lo_u32_b32 v51, -1, 0
	v_mbcnt_hi_u32_b32 v51, -1, v51
	s_nop 0
	v_lshlrev_b32_e32 v51, 2, v51
	v_xor_b32_e32 v51, 32, v51
	ds_bpermute_b32 v51, v51, v50
	s_waitcnt lgkmcnt(0)
	v_add_f32_e32 v50, v50, v51
	v_mbcnt_lo_u32_b32 v51, -1, 0
	v_mbcnt_hi_u32_b32 v51, -1, v51
	s_nop 0
	v_lshlrev_b32_e32 v51, 2, v51
	v_xor_b32_e32 v51, 64, v51
	ds_bpermute_b32 v51, v51, v50
	s_waitcnt lgkmcnt(0)
	v_add_f32_e32 v50, v50, v51
	v_mbcnt_lo_u32_b32 v51, -1, 0
	v_mbcnt_hi_u32_b32 v51, -1, v51
	s_nop 0
	v_lshlrev_b32_e32 v51, 2, v51
	v_xor_b32_e32 v51, 0x80, v51
	ds_bpermute_b32 v51, v51, v50
	s_waitcnt lgkmcnt(0)
	v_add_f32_e32 v56, v50, v51
	v_fmamk_f32 v59, v56, 0xba800000, v47
	v_fmamk_f32 v58, v56, 0xba800000, v46
	v_fmamk_f32 v49, v56, 0xba800000, v49
	v_fmac_f32_e32 v48, 0xba800000, v56
	v_pk_mul_f32 v[46:47], v[48:49], v[48:49]
	v_pk_mul_f32 v[50:51], v[58:59], v[58:59]
	v_fmamk_f32 v45, v56, 0xba800000, v45
	v_pk_mov_b32 v[52:53], v[50:51], v[46:47] op_sel:[1,0]
	v_mov_b32_e32 v51, v47
	v_pk_add_f32 v[46:47], v[52:53], v[50:51]
	v_fmac_f32_e32 v44, 0xba800000, v56
	v_pk_add_f32 v[50:51], v[46:47], v[46:47] op_sel_hi:[0,1]
	v_fmamk_f32 v47, v56, 0xba800000, v43
	v_fmamk_f32 v46, v56, 0xba800000, v42
	v_pk_mul_f32 v[42:43], v[44:45], v[44:45]
	v_pk_mul_f32 v[52:53], v[46:47], v[46:47]
	v_fmac_f32_e32 v40, 0xba800000, v56
	v_pk_mov_b32 v[54:55], v[52:53], v[42:43] op_sel:[1,0]
	v_mov_b32_e32 v53, v43
	v_pk_add_f32 v[42:43], v[54:55], v[52:53]
	v_fmamk_f32 v41, v56, 0xba800000, v41
	v_pk_add_f32 v[52:53], v[42:43], v[42:43] op_sel_hi:[0,1]
	v_fmamk_f32 v42, v56, 0xba800000, v38
	v_fmamk_f32 v43, v56, 0xba800000, v39
	v_mul_f32_e32 v38, v42, v42
	v_pk_fma_f32 v[38:39], v[42:43], v[42:43], v[38:39] op_sel_hi:[1,1,0]
	v_fmamk_f32 v37, v56, 0xba800000, v37
	v_mul_f32_e32 v38, v40, v40
	v_pk_fma_f32 v[54:55], v[40:41], v[40:41], v[38:39] op_sel_hi:[1,1,0]
	v_fmamk_f32 v36, v56, 0xba800000, v36
	v_fmamk_f32 v35, v56, 0xba800000, v35
	v_fmac_f32_e32 v34, 0xba800000, v56
	v_mul_f32_e32 v38, v34, v34
	v_mul_f32_e32 v54, v35, v35
	v_mul_f32_e32 v50, v36, v36
	v_mul_f32_e32 v52, v37, v37
	v_pk_add_f32 v[38:39], v[38:39], v[54:55]
	v_pk_add_f32 v[50:51], v[50:51], v[52:53]
	s_nop 0
	v_pk_add_f32 v[38:39], v[38:39], v[50:51]
	s_nop 0
	v_add_f32_e32 v38, v38, v39
	v_mbcnt_lo_u32_b32 v39, -1, 0
	v_mbcnt_hi_u32_b32 v39, -1, v39
	s_nop 0
	v_lshlrev_b32_e32 v39, 2, v39
	v_xor_b32_e32 v39, 4, v39
	ds_bpermute_b32 v39, v39, v38
	s_waitcnt lgkmcnt(0)
	v_add_f32_e32 v38, v38, v39
	v_mbcnt_lo_u32_b32 v39, -1, 0
	v_mbcnt_hi_u32_b32 v39, -1, v39
	s_nop 0
	v_lshlrev_b32_e32 v39, 2, v39
	v_xor_b32_e32 v39, 8, v39
	ds_bpermute_b32 v39, v39, v38
	s_waitcnt lgkmcnt(0)
	v_add_f32_e32 v38, v38, v39
	v_mbcnt_lo_u32_b32 v39, -1, 0
	v_mbcnt_hi_u32_b32 v39, -1, v39
	s_nop 0
	v_lshlrev_b32_e32 v39, 2, v39
	v_xor_b32_e32 v39, 16, v39
	ds_bpermute_b32 v39, v39, v38
	s_waitcnt lgkmcnt(0)
	v_add_f32_e32 v38, v38, v39
	v_mbcnt_lo_u32_b32 v39, -1, 0
	v_mbcnt_hi_u32_b32 v39, -1, v39
	s_nop 0
	v_lshlrev_b32_e32 v39, 2, v39
	v_xor_b32_e32 v39, 32, v39
	ds_bpermute_b32 v39, v39, v38
	s_waitcnt lgkmcnt(0)
; __device__ __forceinline__ unsigned pk4_fp8(float a, float b, float c, float d) { int w = __builtin_amdgcn_cvt_pk_fp8_f32(a, b, 0, false); w = __builtin_amdgcn_cvt_pk_fp8_f32(c, d, w, true); return (unsigned)w; }
; __device__ __forceinline__ void ln_rows4(const float* x, const float* g, const float* b, f16* h, unsigned char* h8, int m, int stride, int lane) {
;     ...
;         const float mean = wave_sum(s) * (1.f / DM); float s2 = 0.f;
; #pragma unroll
;         for (int j = 0; j < 4; ++j) { v[r][j] = v[r][j] - mean; s2 += (v[r][j].x * v[r][j].x + v[r][j].y * v[r][j].y) + (v[r][j].z * v[r][j].z + v[r][j].w * v[r][j].w); }
;         const float rstd = 1.f / sqrtf(wave_sum(s2) * (1.f / DM) + LN_EPS);
; #pragma unroll
;         for (int j = 0; j < 4; ++j) { const f32x4 gg = ((const f32x4*)g)[lane + 64 * j], bb = ((const f32x4*)b)[lane + 64 * j]; const f32x4 y = v[r][j] * rstd * gg + bb;
;             u32x2 w; w.x = rd<D_H>(pk_f16(y.x, y.y)); w.y = rd<D_H>(pk_f16(y.z, y.w)); ((u32x2*)(h + (size_t)(m + r * stride) * DM))[lane + 64 * j] = w;
;             ((unsigned*)(h8 + (size_t)(m + r * stride) * DM))[lane + 64 * j] = pk4_fp8(y.x, y.y, y.z, y.w); } }
	v_add_f32_e32 v38, v38, v39
	v_mbcnt_lo_u32_b32 v39, -1, 0
	v_mbcnt_hi_u32_b32 v39, -1, v39
	s_nop 0
	v_lshlrev_b32_e32 v39, 2, v39
	v_xor_b32_e32 v39, 64, v39
	ds_bpermute_b32 v39, v39, v38
	s_waitcnt lgkmcnt(0)
	v_add_f32_e32 v38, v38, v39
	v_mbcnt_lo_u32_b32 v39, -1, 0
	v_mbcnt_hi_u32_b32 v39, -1, v39
	s_nop 0
	v_lshlrev_b32_e32 v39, 2, v39
	v_xor_b32_e32 v39, 0x80, v39
	ds_bpermute_b32 v39, v39, v38
	s_waitcnt lgkmcnt(0)
	v_add_f32_e32 v38, v38, v39
	v_fmamk_f32 v38, v38, 0x3a800000, v223
	v_cmp_gt_f32_e32 vcc, s7, v38
	v_mul_f32_e32 v39, 0x4f800000, v38
	s_nop 0
	v_cndmask_b32_e32 v38, v38, v39, vcc
	v_sqrt_f32_e32 v39, v38
	s_nop 0
	v_add_u32_e32 v50, -1, v39
	v_fma_f32 v51, -v50, v39, v38
	v_cmp_ge_f32_e64 s[4:5], 0, v51
	v_add_u32_e32 v51, 1, v39
	s_nop 0
	v_cndmask_b32_e64 v50, v39, v50, s[4:5]
	v_fma_f32 v39, -v51, v39, v38
	v_cmp_lt_f32_e64 s[4:5], 0, v39
	s_nop 1
	v_cndmask_b32_e64 v39, v50, v51, s[4:5]
	v_mul_f32_e32 v50, 0x37800000, v39
	v_cndmask_b32_e32 v39, v39, v50, vcc
	v_cmp_class_f32_e32 vcc, v38, v224
	s_nop 1
	v_cndmask_b32_e32 v38, v39, v38, vcc
	v_div_scale_f32 v39, s[4:5], v38, v38, 1.0
	v_rcp_f32_e32 v50, v39
	s_nop 0
	v_fma_f32 v51, -v39, v50, 1.0
	v_fmac_f32_e32 v50, v51, v50
	v_div_scale_f32 v51, vcc, 1.0, v38, 1.0
	v_mul_f32_e32 v52, v51, v50
	v_fma_f32 v53, -v39, v52, v51
	v_fmac_f32_e32 v52, v53, v50
	v_fma_f32 v39, -v39, v52, v51
	v_div_fmas_f32 v39, v39, v50, v52
	v_div_fixup_f32 v38, v39, v38, 1.0
	v_pk_mul_f32 v[58:59], v[58:59], v[38:39] op_sel_hi:[1,0]
	v_pk_mul_f32 v[48:49], v[48:49], v[38:39] op_sel_hi:[1,0]
	v_pk_fma_f32 v[50:51], v[96:97], v[58:59], v[112:113]
	s_nop 0
	v_cvt_pk_f16_f32 v39, v50, v51
	v_pk_fma_f32 v[48:49], v[98:99], v[48:49], v[114:115]
	v_add_u32_e32 v39, 0x20002, v39
	v_and_b32_e32 v52, 0xfffcfffc, v39
	v_cvt_pk_f16_f32 v39, v48, v49
	v_add_u32_e32 v39, 0x20002, v39
	v_and_b32_e32 v53, 0xfffcfffc, v39
	v_mov_b32_e32 v39, v33
	v_cvt_pk_fp8_f32 v39, v50, v51
	v_lshl_add_u64 v[54:55], s[54:55], 0, v[80:81]
	v_add_co_u32_e32 v58, vcc, s11, v54
	v_cvt_pk_fp8_f32 v39, v48, v49 op_sel:[0,0,1]
	s_nop 0
	v_addc_co_u32_e32 v59, vcc, 0, v55, vcc
	v_lshl_add_u64 v[48:49], s[54:55], 0, v[78:79]
	v_add_co_u32_e32 v48, vcc, s18, v48
	global_store_dwordx2 v[58:59], v[52:53], off
	s_nop 0
	v_addc_co_u32_e32 v49, vcc, 0, v49, vcc
	global_store_dword v[48:49], v39, off
	v_pk_mul_f32 v[46:47], v[46:47], v[38:39] op_sel_hi:[1,0]
	v_pk_mul_f32 v[44:45], v[44:45], v[38:39] op_sel_hi:[1,0]
	v_lshl_add_u64 v[78:79], v[78:79], 0, s[80:81]
	v_lshl_add_u64 v[80:81], v[80:81], 0, s[74:75]
	v_pk_fma_f32 v[46:47], v[100:101], v[46:47], v[116:117]
	s_nop 0
	v_cvt_pk_f16_f32 v39, v46, v47
	v_pk_fma_f32 v[44:45], v[102:103], v[44:45], v[118:119]
	v_add_u32_e32 v39, 0x20002, v39
	v_and_b32_e32 v50, 0xfffcfffc, v39
	v_cvt_pk_f16_f32 v39, v44, v45
	v_add_u32_e32 v39, 0x20002, v39
	v_and_b32_e32 v51, 0xfffcfffc, v39
	v_mov_b32_e32 v39, v33
	v_cvt_pk_fp8_f32 v39, v46, v47
	global_store_dwordx2 v[58:59], v[50:51], off offset:512
	v_cvt_pk_fp8_f32 v39, v44, v45 op_sel:[0,0,1]
	global_store_dword v[48:49], v39, off offset:256
	v_pk_mul_f32 v[42:43], v[42:43], v[38:39] op_sel_hi:[1,0]
	v_pk_mul_f32 v[40:41], v[40:41], v[38:39] op_sel_hi:[1,0]
	v_pk_fma_f32 v[42:43], v[104:105], v[42:43], v[120:121]
	s_nop 0
	v_cvt_pk_f16_f32 v39, v42, v43
	v_pk_fma_f32 v[40:41], v[106:107], v[40:41], v[122:123]
	v_add_u32_e32 v39, 0x20002, v39
	v_and_b32_e32 v44, 0xfffcfffc, v39
	v_cvt_pk_f16_f32 v39, v40, v41
	v_add_u32_e32 v39, 0x20002, v39
	v_and_b32_e32 v45, 0xfffcfffc, v39
	v_mov_b32_e32 v39, v33
	v_cvt_pk_fp8_f32 v39, v42, v43
	global_store_dwordx2 v[58:59], v[44:45], off offset:1024
	v_cvt_pk_fp8_f32 v39, v40, v41 op_sel:[0,0,1]
	global_store_dword v[48:49], v39, off offset:512
	v_pk_mul_f32 v[34:35], v[34:35], v[38:39] op_sel_hi:[1,0]
	v_pk_mul_f32 v[36:37], v[36:37], v[38:39] op_sel_hi:[1,0]
	v_pk_fma_f32 v[34:35], v[34:35], v[108:109], v[124:125]
	v_pk_fma_f32 v[36:37], v[36:37], v[110:111], v[126:127]
	v_cvt_pk_f16_f32 v38, v34, v35
	v_cvt_pk_f16_f32 v39, v36, v37
	v_add_u32_e32 v38, 0x20002, v38
	v_add_u32_e32 v39, 0x20002, v39
	v_and_b32_e32 v38, 0xfffcfffc, v38
	v_and_b32_e32 v39, 0xfffcfffc, v39
	global_store_dwordx2 v[58:59], v[38:39], off offset:1536
	v_mov_b32_e32 v38, v33
	v_cvt_pk_fp8_f32 v38, v34, v35
	v_mov_b32_e32 v34, v29
	v_mov_b32_e32 v35, v30
	v_mov_b32_e32 v39, v27
	v_cvt_pk_fp8_f32 v38, v36, v37 op_sel:[0,0,1]
	v_mov_b32_e32 v36, v28
	v_mov_b32_e32 v37, v31
	v_pk_add_f32 v[34:35], v[34:35], v[36:37]
	global_store_dword v[48:49], v38, off offset:768
	v_mov_b32_e32 v36, v25
	v_mov_b32_e32 v37, v26
	v_mov_b32_e32 v38, v24
	v_pk_add_f32 v[36:37], v[36:37], v[38:39]
	v_add_f32_e32 v34, v34, v35
	v_pk_add_f32 v[36:37], v[36:37], v[36:37] op_sel:[0,1] op_sel_hi:[1,0]
	v_add_f32_e32 v34, 0, v34
	v_add_f32_e32 v38, v20, v21
	v_add_f32_e32 v40, v22, v23
	v_mov_b32_e32 v35, v16
	v_mov_b32_e32 v37, v17
	v_mov_b32_e32 v39, v18
	v_mov_b32_e32 v41, v19
	v_pk_add_f32 v[34:35], v[34:35], v[36:37]
	v_pk_add_f32 v[36:37], v[38:39], v[40:41]
	s_nop 0
	v_pk_add_f32 v[34:35], v[34:35], v[36:37]
	s_nop 0
	v_add_f32_e32 v34, v34, v35
	v_mbcnt_lo_u32_b32 v35, -1, 0
	v_mbcnt_hi_u32_b32 v35, -1, v35
	s_nop 0
	v_lshlrev_b32_e32 v35, 2, v35
	v_xor_b32_e32 v35, 4, v35
	ds_bpermute_b32 v35, v35, v34
	s_waitcnt lgkmcnt(0)
	v_add_f32_e32 v34, v34, v35
	v_mbcnt_lo_u32_b32 v35, -1, 0
	v_mbcnt_hi_u32_b32 v35, -1, v35
	s_nop 0
	v_lshlrev_b32_e32 v35, 2, v35
	v_xor_b32_e32 v35, 8, v35
	ds_bpermute_b32 v35, v35, v34
	s_waitcnt lgkmcnt(0)
; __device__ __forceinline__ unsigned pk4_fp8(float a, float b, float c, float d) { int w = __builtin_amdgcn_cvt_pk_fp8_f32(a, b, 0, false); w = __builtin_amdgcn_cvt_pk_fp8_f32(c, d, w, true); return (unsigned)w; }
; __device__ __forceinline__ void ln_rows4(const float* x, const float* g, const float* b, f16* h, unsigned char* h8, int m, int stride, int lane) {
;     ...
;         const float mean = wave_sum(s) * (1.f / DM); float s2 = 0.f;
; #pragma unroll
;         for (int j = 0; j < 4; ++j) { v[r][j] = v[r][j] - mean; s2 += (v[r][j].x * v[r][j].x + v[r][j].y * v[r][j].y) + (v[r][j].z * v[r][j].z + v[r][j].w * v[r][j].w); }
;         const float rstd = 1.f / sqrtf(wave_sum(s2) * (1.f / DM) + LN_EPS);
; #pragma unroll
;         for (int j = 0; j < 4; ++j) { const f32x4 gg = ((const f32x4*)g)[lane + 64 * j], bb = ((const f32x4*)b)[lane + 64 * j]; const f32x4 y = v[r][j] * rstd * gg + bb;
;             u32x2 w; w.x = rd<D_H>(pk_f16(y.x, y.y)); w.y = rd<D_H>(pk_f16(y.z, y.w)); ((u32x2*)(h + (size_t)(m + r * stride) * DM))[lane + 64 * j] = w;
;             ((unsigned*)(h8 + (size_t)(m + r * stride) * DM))[lane + 64 * j] = pk4_fp8(y.x, y.y, y.z, y.w); } }
	v_add_f32_e32 v34, v34, v35
	v_mbcnt_lo_u32_b32 v35, -1, 0
	v_mbcnt_hi_u32_b32 v35, -1, v35
	s_nop 0
	v_lshlrev_b32_e32 v35, 2, v35
	v_xor_b32_e32 v35, 16, v35
	ds_bpermute_b32 v35, v35, v34
	s_waitcnt lgkmcnt(0)
	v_add_f32_e32 v34, v34, v35
	v_mbcnt_lo_u32_b32 v35, -1, 0
	v_mbcnt_hi_u32_b32 v35, -1, v35
	s_nop 0
	v_lshlrev_b32_e32 v35, 2, v35
	v_xor_b32_e32 v35, 32, v35
	ds_bpermute_b32 v35, v35, v34
	s_waitcnt lgkmcnt(0)
	v_add_f32_e32 v34, v34, v35
	v_mbcnt_lo_u32_b32 v35, -1, 0
	v_mbcnt_hi_u32_b32 v35, -1, v35
	s_nop 0
	v_lshlrev_b32_e32 v35, 2, v35
	v_xor_b32_e32 v35, 64, v35
	ds_bpermute_b32 v35, v35, v34
	s_waitcnt lgkmcnt(0)
	v_add_f32_e32 v34, v34, v35
	v_mbcnt_lo_u32_b32 v35, -1, 0
	v_mbcnt_hi_u32_b32 v35, -1, v35
	s_nop 0
	v_lshlrev_b32_e32 v35, 2, v35
	v_xor_b32_e32 v35, 0x80, v35
	ds_bpermute_b32 v35, v35, v34
	s_waitcnt lgkmcnt(0)
	v_add_f32_e32 v40, v34, v35
	v_fmamk_f32 v45, v40, 0xba800000, v29
	v_fmamk_f32 v44, v40, 0xba800000, v28
	v_fmamk_f32 v31, v40, 0xba800000, v31
	v_fmac_f32_e32 v30, 0xba800000, v40
	v_pk_mul_f32 v[28:29], v[30:31], v[30:31]
	v_pk_mul_f32 v[34:35], v[44:45], v[44:45]
	v_fmamk_f32 v27, v40, 0xba800000, v27
	v_pk_mov_b32 v[36:37], v[34:35], v[28:29] op_sel:[1,0]
	v_mov_b32_e32 v35, v29
	v_pk_add_f32 v[28:29], v[36:37], v[34:35]
	v_fmamk_f32 v35, v40, 0xba800000, v25
	v_fmamk_f32 v34, v40, 0xba800000, v24
	v_fmac_f32_e32 v26, 0xba800000, v40
	v_pk_add_f32 v[36:37], v[28:29], v[28:29] op_sel_hi:[0,1]
	v_pk_mul_f32 v[24:25], v[26:27], v[26:27]
	v_pk_mul_f32 v[28:29], v[34:35], v[34:35]
	v_fmac_f32_e32 v22, 0xba800000, v40
	v_pk_mov_b32 v[38:39], v[28:29], v[24:25] op_sel:[1,0]
	v_mov_b32_e32 v29, v25
	v_pk_add_f32 v[24:25], v[38:39], v[28:29]
	v_fmamk_f32 v28, v40, 0xba800000, v20
	v_fmamk_f32 v29, v40, 0xba800000, v21
	v_mul_f32_e32 v20, v28, v28
	v_pk_fma_f32 v[20:21], v[28:29], v[28:29], v[20:21] op_sel_hi:[1,1,0]
	v_fmamk_f32 v23, v40, 0xba800000, v23
	v_mul_f32_e32 v20, v22, v22
	v_pk_add_f32 v[24:25], v[24:25], v[24:25] op_sel_hi:[0,1]
	v_pk_fma_f32 v[38:39], v[22:23], v[22:23], v[20:21] op_sel_hi:[1,1,0]
	v_fmamk_f32 v19, v40, 0xba800000, v19
	v_fmamk_f32 v18, v40, 0xba800000, v18
	v_fmamk_f32 v17, v40, 0xba800000, v17
	v_fmac_f32_e32 v16, 0xba800000, v40
	v_mul_f32_e32 v20, v16, v16
	v_mul_f32_e32 v38, v17, v17
	v_mul_f32_e32 v36, v18, v18
	v_mul_f32_e32 v24, v19, v19
	v_pk_add_f32 v[20:21], v[20:21], v[38:39]
	v_pk_add_f32 v[24:25], v[36:37], v[24:25]
	s_nop 0
	v_pk_add_f32 v[20:21], v[20:21], v[24:25]
	s_nop 0
	v_add_f32_e32 v20, v20, v21
	v_mbcnt_lo_u32_b32 v21, -1, 0
	v_mbcnt_hi_u32_b32 v21, -1, v21
	s_nop 0
	v_lshlrev_b32_e32 v21, 2, v21
	v_xor_b32_e32 v21, 4, v21
	ds_bpermute_b32 v21, v21, v20
	s_waitcnt lgkmcnt(0)
	v_add_f32_e32 v20, v20, v21
	v_mbcnt_lo_u32_b32 v21, -1, 0
	v_mbcnt_hi_u32_b32 v21, -1, v21
	s_nop 0
	v_lshlrev_b32_e32 v21, 2, v21
	v_xor_b32_e32 v21, 8, v21
	ds_bpermute_b32 v21, v21, v20
	s_waitcnt lgkmcnt(0)
	v_add_f32_e32 v20, v20, v21
	v_mbcnt_lo_u32_b32 v21, -1, 0
	v_mbcnt_hi_u32_b32 v21, -1, v21
	s_nop 0
	v_lshlrev_b32_e32 v21, 2, v21
	v_xor_b32_e32 v21, 16, v21
	ds_bpermute_b32 v21, v21, v20
	s_waitcnt lgkmcnt(0)
	v_add_f32_e32 v20, v20, v21
	v_mbcnt_lo_u32_b32 v21, -1, 0
	v_mbcnt_hi_u32_b32 v21, -1, v21
	s_nop 0
	v_lshlrev_b32_e32 v21, 2, v21
	v_xor_b32_e32 v21, 32, v21
	ds_bpermute_b32 v21, v21, v20
	s_waitcnt lgkmcnt(0)
	v_add_f32_e32 v20, v20, v21
	v_mbcnt_lo_u32_b32 v21, -1, 0
	v_mbcnt_hi_u32_b32 v21, -1, v21
	s_nop 0
	v_lshlrev_b32_e32 v21, 2, v21
	v_xor_b32_e32 v21, 64, v21
	ds_bpermute_b32 v21, v21, v20
	s_waitcnt lgkmcnt(0)
	v_add_f32_e32 v20, v20, v21
	v_mbcnt_lo_u32_b32 v21, -1, 0
	v_mbcnt_hi_u32_b32 v21, -1, v21
	s_nop 0
	v_lshlrev_b32_e32 v21, 2, v21
	v_xor_b32_e32 v21, 0x80, v21
	ds_bpermute_b32 v21, v21, v20
	s_waitcnt lgkmcnt(0)
	v_add_f32_e32 v20, v20, v21
	v_fmamk_f32 v20, v20, 0x3a800000, v223
	v_cmp_gt_f32_e32 vcc, s7, v20
	v_mul_f32_e32 v21, 0x4f800000, v20
	s_nop 0
	v_cndmask_b32_e32 v20, v20, v21, vcc
	v_sqrt_f32_e32 v21, v20
	s_nop 0
	v_add_u32_e32 v24, -1, v21
	v_fma_f32 v25, -v24, v21, v20
	v_cmp_ge_f32_e64 s[4:5], 0, v25
	v_add_u32_e32 v25, 1, v21
	s_nop 0
	v_cndmask_b32_e64 v24, v21, v24, s[4:5]
	v_fma_f32 v21, -v25, v21, v20
	v_cmp_lt_f32_e64 s[4:5], 0, v21
	s_nop 1
	v_cndmask_b32_e64 v21, v24, v25, s[4:5]
	v_mul_f32_e32 v24, 0x37800000, v21
	v_cndmask_b32_e32 v21, v21, v24, vcc
	v_cmp_class_f32_e32 vcc, v20, v224
	s_nop 1
	v_cndmask_b32_e32 v20, v21, v20, vcc
	v_div_scale_f32 v21, s[4:5], v20, v20, 1.0
	v_rcp_f32_e32 v24, v21
	s_lshl_b64 s[4:5], s[16:17], 10
	s_lshl_b64 s[16:17], s[16:17], 11
	v_fma_f32 v25, -v21, v24, 1.0
	v_fmac_f32_e32 v24, v25, v24
	v_div_scale_f32 v25, vcc, 1.0, v20, 1.0
	v_mul_f32_e32 v36, v25, v24
	v_fma_f32 v37, -v21, v36, v25
	v_fmac_f32_e32 v36, v37, v24
	v_fma_f32 v21, -v21, v36, v25
	v_div_fmas_f32 v21, v21, v24, v36
	v_div_fixup_f32 v20, v21, v20, 1.0
	v_pk_mul_f32 v[24:25], v[44:45], v[20:21] op_sel_hi:[1,0]
	v_pk_mul_f32 v[30:31], v[30:31], v[20:21] op_sel_hi:[1,0]
	v_pk_fma_f32 v[36:37], v[96:97], v[24:25], v[112:113]
	s_nop 0
	v_cvt_pk_f16_f32 v21, v36, v37
	v_pk_fma_f32 v[30:31], v[98:99], v[30:31], v[114:115]
	v_add_u32_e32 v21, 0x20002, v21
	v_and_b32_e32 v38, 0xfffcfffc, v21
	v_cvt_pk_f16_f32 v21, v30, v31
	v_add_u32_e32 v21, 0x20002, v21
	v_and_b32_e32 v39, 0xfffcfffc, v21
	v_mov_b32_e32 v21, v33
	v_cvt_pk_fp8_f32 v21, v36, v37
	v_lshl_add_u64 v[24:25], v[68:69], 0, s[16:17]
	global_store_dwordx2 v[24:25], v[38:39], off
	v_cvt_pk_fp8_f32 v21, v30, v31 op_sel:[0,0,1]
	v_lshl_add_u64 v[30:31], v[72:73], 0, s[4:5]
	global_store_dword v[30:31], v21, off
	v_pk_mul_f32 v[34:35], v[34:35], v[20:21] op_sel_hi:[1,0]
; __device__ __forceinline__ unsigned pk4_fp8(float a, float b, float c, float d) { int w = __builtin_amdgcn_cvt_pk_fp8_f32(a, b, 0, false); w = __builtin_amdgcn_cvt_pk_fp8_f32(c, d, w, true); return (unsigned)w; }
; __device__ __forceinline__ void ln_rows4(const float* x, const float* g, const float* b, f16* h, unsigned char* h8, int m, int stride, int lane) {
;     ...
;         const float mean = wave_sum(s) * (1.f / DM); float s2 = 0.f;
; #pragma unroll
;         for (int j = 0; j < 4; ++j) { v[r][j] = v[r][j] - mean; s2 += (v[r][j].x * v[r][j].x + v[r][j].y * v[r][j].y) + (v[r][j].z * v[r][j].z + v[r][j].w * v[r][j].w); }
;         const float rstd = 1.f / sqrtf(wave_sum(s2) * (1.f / DM) + LN_EPS);
; #pragma unroll
;         for (int j = 0; j < 4; ++j) { const f32x4 gg = ((const f32x4*)g)[lane + 64 * j], bb = ((const f32x4*)b)[lane + 64 * j]; const f32x4 y = v[r][j] * rstd * gg + bb;
;             u32x2 w; w.x = rd<D_H>(pk_f16(y.x, y.y)); w.y = rd<D_H>(pk_f16(y.z, y.w)); ((u32x2*)(h + (size_t)(m + r * stride) * DM))[lane + 64 * j] = w;
;             ((unsigned*)(h8 + (size_t)(m + r * stride) * DM))[lane + 64 * j] = pk4_fp8(y.x, y.y, y.z, y.w); } }
	v_pk_mul_f32 v[26:27], v[26:27], v[20:21] op_sel_hi:[1,0]
	v_pk_fma_f32 v[34:35], v[100:101], v[34:35], v[116:117]
	s_nop 0
	v_cvt_pk_f16_f32 v21, v34, v35
	v_pk_fma_f32 v[26:27], v[102:103], v[26:27], v[118:119]
	v_add_u32_e32 v21, 0x20002, v21
	v_and_b32_e32 v36, 0xfffcfffc, v21
	v_cvt_pk_f16_f32 v21, v26, v27
	v_add_u32_e32 v21, 0x20002, v21
	v_and_b32_e32 v37, 0xfffcfffc, v21
	v_mov_b32_e32 v21, v33
	v_cvt_pk_fp8_f32 v21, v34, v35
	global_store_dwordx2 v[24:25], v[36:37], off offset:512
	v_cvt_pk_fp8_f32 v21, v26, v27 op_sel:[0,0,1]
	global_store_dword v[30:31], v21, off offset:256
	v_pk_mul_f32 v[26:27], v[28:29], v[20:21] op_sel_hi:[1,0]
	v_pk_mul_f32 v[22:23], v[22:23], v[20:21] op_sel_hi:[1,0]
	v_pk_fma_f32 v[26:27], v[104:105], v[26:27], v[120:121]
	s_nop 0
	v_cvt_pk_f16_f32 v21, v26, v27
	v_pk_fma_f32 v[22:23], v[106:107], v[22:23], v[122:123]
	v_add_u32_e32 v21, 0x20002, v21
	v_and_b32_e32 v28, 0xfffcfffc, v21
	v_cvt_pk_f16_f32 v21, v22, v23
	v_add_u32_e32 v21, 0x20002, v21
	v_and_b32_e32 v29, 0xfffcfffc, v21
	v_mov_b32_e32 v21, v33
	v_cvt_pk_fp8_f32 v21, v26, v27
	global_store_dwordx2 v[24:25], v[28:29], off offset:1024
	v_cvt_pk_fp8_f32 v21, v22, v23 op_sel:[0,0,1]
	v_add_f32_e32 v22, v6, v7
	v_mov_b32_e32 v23, v3
	global_store_dword v[30:31], v21, off offset:512
	v_pk_mul_f32 v[16:17], v[16:17], v[20:21] op_sel_hi:[1,0]
	v_pk_mul_f32 v[18:19], v[18:19], v[20:21] op_sel_hi:[1,0]
	v_pk_fma_f32 v[16:17], v[16:17], v[108:109], v[124:125]
	v_pk_fma_f32 v[18:19], v[18:19], v[110:111], v[126:127]
	v_cvt_pk_f16_f32 v20, v16, v17
	v_cvt_pk_f16_f32 v21, v18, v19
	v_add_u32_e32 v20, 0x20002, v20
	v_add_u32_e32 v21, 0x20002, v21
	v_and_b32_e32 v20, 0xfffcfffc, v20
	v_and_b32_e32 v21, 0xfffcfffc, v21
	global_store_dwordx2 v[24:25], v[20:21], off offset:1536
	v_mov_b32_e32 v20, v33
	v_cvt_pk_fp8_f32 v20, v16, v17
	v_mov_b32_e32 v16, v13
	v_mov_b32_e32 v17, v14
	v_mov_b32_e32 v21, v11
	v_cvt_pk_fp8_f32 v20, v18, v19 op_sel:[0,0,1]
	v_mov_b32_e32 v18, v12
	v_mov_b32_e32 v19, v15
	v_pk_add_f32 v[16:17], v[16:17], v[18:19]
	global_store_dword v[30:31], v20, off offset:768
	v_mov_b32_e32 v18, v9
	v_mov_b32_e32 v19, v10
	v_mov_b32_e32 v20, v8
	v_pk_add_f32 v[18:19], v[18:19], v[20:21]
	v_add_f32_e32 v16, v16, v17
	v_pk_add_f32 v[18:19], v[18:19], v[18:19] op_sel:[0,1] op_sel_hi:[1,0]
	v_add_f32_e32 v16, 0, v16
	v_add_f32_e32 v20, v4, v5
	v_mov_b32_e32 v17, v0
	v_mov_b32_e32 v19, v1
	v_mov_b32_e32 v21, v2
	v_pk_add_f32 v[16:17], v[16:17], v[18:19]
	v_pk_add_f32 v[18:19], v[20:21], v[22:23]
	s_nop 0
	v_pk_add_f32 v[16:17], v[16:17], v[18:19]
	s_nop 0
	v_add_f32_e32 v16, v16, v17
	v_mbcnt_lo_u32_b32 v17, -1, 0
	v_mbcnt_hi_u32_b32 v17, -1, v17
	s_nop 0
	v_lshlrev_b32_e32 v17, 2, v17
	v_xor_b32_e32 v17, 4, v17
	ds_bpermute_b32 v17, v17, v16
	s_waitcnt lgkmcnt(0)
	v_add_f32_e32 v16, v16, v17
	v_mbcnt_lo_u32_b32 v17, -1, 0
	v_mbcnt_hi_u32_b32 v17, -1, v17
	s_nop 0
	v_lshlrev_b32_e32 v17, 2, v17
	v_xor_b32_e32 v17, 8, v17
	ds_bpermute_b32 v17, v17, v16
	s_waitcnt lgkmcnt(0)
	v_add_f32_e32 v16, v16, v17
	v_mbcnt_lo_u32_b32 v17, -1, 0
	v_mbcnt_hi_u32_b32 v17, -1, v17
	s_nop 0
	v_lshlrev_b32_e32 v17, 2, v17
	v_xor_b32_e32 v17, 16, v17
	ds_bpermute_b32 v17, v17, v16
	s_waitcnt lgkmcnt(0)
	v_add_f32_e32 v16, v16, v17
	v_mbcnt_lo_u32_b32 v17, -1, 0
	v_mbcnt_hi_u32_b32 v17, -1, v17
	s_nop 0
	v_lshlrev_b32_e32 v17, 2, v17
	v_xor_b32_e32 v17, 32, v17
	ds_bpermute_b32 v17, v17, v16
	s_waitcnt lgkmcnt(0)
	v_add_f32_e32 v16, v16, v17
	v_mbcnt_lo_u32_b32 v17, -1, 0
	v_mbcnt_hi_u32_b32 v17, -1, v17
	s_nop 0
	v_lshlrev_b32_e32 v17, 2, v17
	v_xor_b32_e32 v17, 64, v17
	ds_bpermute_b32 v17, v17, v16
	s_waitcnt lgkmcnt(0)
	v_add_f32_e32 v16, v16, v17
	v_mbcnt_lo_u32_b32 v17, -1, 0
	v_mbcnt_hi_u32_b32 v17, -1, v17
	s_nop 0
	v_lshlrev_b32_e32 v17, 2, v17
	v_xor_b32_e32 v17, 0x80, v17
	ds_bpermute_b32 v17, v17, v16
	s_waitcnt lgkmcnt(0)
	v_add_f32_e32 v22, v16, v17
	v_fmamk_f32 v27, v22, 0xba800000, v13
	v_fmamk_f32 v26, v22, 0xba800000, v12
	v_fmamk_f32 v15, v22, 0xba800000, v15
	v_fmac_f32_e32 v14, 0xba800000, v22
	v_pk_mul_f32 v[12:13], v[14:15], v[14:15]
	v_pk_mul_f32 v[16:17], v[26:27], v[26:27]
	v_fmamk_f32 v11, v22, 0xba800000, v11
	v_pk_mov_b32 v[18:19], v[16:17], v[12:13] op_sel:[1,0]
	v_mov_b32_e32 v17, v13
	v_pk_add_f32 v[12:13], v[18:19], v[16:17]
	v_fmamk_f32 v17, v22, 0xba800000, v9
	v_fmamk_f32 v16, v22, 0xba800000, v8
	v_fmac_f32_e32 v10, 0xba800000, v22
	v_pk_add_f32 v[18:19], v[12:13], v[12:13] op_sel_hi:[0,1]
	v_pk_mul_f32 v[8:9], v[10:11], v[10:11]
	v_pk_mul_f32 v[12:13], v[16:17], v[16:17]
	v_fmac_f32_e32 v6, 0xba800000, v22
	v_pk_mov_b32 v[20:21], v[12:13], v[8:9] op_sel:[1,0]
	v_mov_b32_e32 v13, v9
	v_pk_add_f32 v[8:9], v[20:21], v[12:13]
	v_fmamk_f32 v12, v22, 0xba800000, v4
	v_fmamk_f32 v13, v22, 0xba800000, v5
	v_mul_f32_e32 v4, v12, v12
	v_pk_fma_f32 v[4:5], v[12:13], v[12:13], v[4:5] op_sel_hi:[1,1,0]
	v_fmamk_f32 v7, v22, 0xba800000, v7
	v_mul_f32_e32 v4, v6, v6
	v_pk_add_f32 v[8:9], v[8:9], v[8:9] op_sel_hi:[0,1]
	v_pk_fma_f32 v[20:21], v[6:7], v[6:7], v[4:5] op_sel_hi:[1,1,0]
	v_fmamk_f32 v3, v22, 0xba800000, v3
	v_fmamk_f32 v2, v22, 0xba800000, v2
	v_fmamk_f32 v1, v22, 0xba800000, v1
	v_fmac_f32_e32 v0, 0xba800000, v22
	v_mul_f32_e32 v4, v0, v0
	v_mul_f32_e32 v20, v1, v1
	v_mul_f32_e32 v18, v2, v2
	v_mul_f32_e32 v8, v3, v3
	v_pk_add_f32 v[4:5], v[4:5], v[20:21]
	v_pk_add_f32 v[8:9], v[18:19], v[8:9]
	s_nop 0
	v_pk_add_f32 v[4:5], v[4:5], v[8:9]
	s_nop 0
	v_add_f32_e32 v4, v4, v5
	v_mbcnt_lo_u32_b32 v5, -1, 0
	v_mbcnt_hi_u32_b32 v5, -1, v5
	s_nop 0
	v_lshlrev_b32_e32 v5, 2, v5
	v_xor_b32_e32 v5, 4, v5
	ds_bpermute_b32 v5, v5, v4
	s_waitcnt lgkmcnt(0)
; __device__ __forceinline__ unsigned pk4_fp8(float a, float b, float c, float d) { int w = __builtin_amdgcn_cvt_pk_fp8_f32(a, b, 0, false); w = __builtin_amdgcn_cvt_pk_fp8_f32(c, d, w, true); return (unsigned)w; }
; __device__ __forceinline__ void ln_rows4(const float* x, const float* g, const float* b, f16* h, unsigned char* h8, int m, int stride, int lane) {
;     ...
;         const float mean = wave_sum(s) * (1.f / DM); float s2 = 0.f;
; #pragma unroll
;         for (int j = 0; j < 4; ++j) { v[r][j] = v[r][j] - mean; s2 += (v[r][j].x * v[r][j].x + v[r][j].y * v[r][j].y) + (v[r][j].z * v[r][j].z + v[r][j].w * v[r][j].w); }
;         const float rstd = 1.f / sqrtf(wave_sum(s2) * (1.f / DM) + LN_EPS);
; #pragma unroll
;         for (int j = 0; j < 4; ++j) { const f32x4 gg = ((const f32x4*)g)[lane + 64 * j], bb = ((const f32x4*)b)[lane + 64 * j]; const f32x4 y = v[r][j] * rstd * gg + bb;
;             u32x2 w; w.x = rd<D_H>(pk_f16(y.x, y.y)); w.y = rd<D_H>(pk_f16(y.z, y.w)); ((u32x2*)(h + (size_t)(m + r * stride) * DM))[lane + 64 * j] = w;
;             ((unsigned*)(h8 + (size_t)(m + r * stride) * DM))[lane + 64 * j] = pk4_fp8(y.x, y.y, y.z, y.w); } }
	v_add_f32_e32 v4, v4, v5
	v_mbcnt_lo_u32_b32 v5, -1, 0
	v_mbcnt_hi_u32_b32 v5, -1, v5
	s_nop 0
	v_lshlrev_b32_e32 v5, 2, v5
	v_xor_b32_e32 v5, 8, v5
	ds_bpermute_b32 v5, v5, v4
	s_waitcnt lgkmcnt(0)
	v_add_f32_e32 v4, v4, v5
	v_mbcnt_lo_u32_b32 v5, -1, 0
	v_mbcnt_hi_u32_b32 v5, -1, v5
	s_nop 0
	v_lshlrev_b32_e32 v5, 2, v5
	v_xor_b32_e32 v5, 16, v5
	ds_bpermute_b32 v5, v5, v4
	s_waitcnt lgkmcnt(0)
	v_add_f32_e32 v4, v4, v5
	v_mbcnt_lo_u32_b32 v5, -1, 0
	v_mbcnt_hi_u32_b32 v5, -1, v5
	s_nop 0
	v_lshlrev_b32_e32 v5, 2, v5
	v_xor_b32_e32 v5, 32, v5
	ds_bpermute_b32 v5, v5, v4
	s_waitcnt lgkmcnt(0)
	v_add_f32_e32 v4, v4, v5
	v_mbcnt_lo_u32_b32 v5, -1, 0
	v_mbcnt_hi_u32_b32 v5, -1, v5
	s_nop 0
	v_lshlrev_b32_e32 v5, 2, v5
	v_xor_b32_e32 v5, 64, v5
	ds_bpermute_b32 v5, v5, v4
	s_waitcnt lgkmcnt(0)
	v_add_f32_e32 v4, v4, v5
	v_mbcnt_lo_u32_b32 v5, -1, 0
	v_mbcnt_hi_u32_b32 v5, -1, v5
	s_nop 0
	v_lshlrev_b32_e32 v5, 2, v5
	v_xor_b32_e32 v5, 0x80, v5
	ds_bpermute_b32 v5, v5, v4
	s_waitcnt lgkmcnt(0)
	v_add_f32_e32 v4, v4, v5
	v_fmamk_f32 v4, v4, 0x3a800000, v223
	v_cmp_gt_f32_e32 vcc, s7, v4
	v_mul_f32_e32 v5, 0x4f800000, v4
	s_nop 0
	v_cndmask_b32_e32 v4, v4, v5, vcc
	v_sqrt_f32_e32 v5, v4
	s_nop 0
	v_add_u32_e32 v8, -1, v5
	v_fma_f32 v9, -v8, v5, v4
	v_cmp_ge_f32_e64 s[4:5], 0, v9
	v_add_u32_e32 v9, 1, v5
	s_nop 0
	v_cndmask_b32_e64 v8, v5, v8, s[4:5]
	v_fma_f32 v5, -v9, v5, v4
	v_cmp_lt_f32_e64 s[4:5], 0, v5
	s_nop 1
	v_cndmask_b32_e64 v5, v8, v9, s[4:5]
	v_mul_f32_e32 v8, 0x37800000, v5
	v_cndmask_b32_e32 v5, v5, v8, vcc
	v_cmp_class_f32_e32 vcc, v4, v224
	s_nop 1
	v_cndmask_b32_e32 v4, v5, v4, vcc
	v_div_scale_f32 v5, s[4:5], v4, v4, 1.0
	v_rcp_f32_e32 v8, v5
	s_lshl_b64 s[4:5], s[14:15], 10
	s_lshl_b64 s[14:15], s[14:15], 11
	v_fma_f32 v9, -v5, v8, 1.0
	v_fmac_f32_e32 v8, v9, v8
	v_div_scale_f32 v9, vcc, 1.0, v4, 1.0
	v_mul_f32_e32 v18, v9, v8
	v_fma_f32 v19, -v5, v18, v9
	v_fmac_f32_e32 v18, v19, v8
	v_fma_f32 v5, -v5, v18, v9
	v_div_fmas_f32 v5, v5, v8, v18
	v_div_fixup_f32 v4, v5, v4, 1.0
	v_pk_mul_f32 v[8:9], v[26:27], v[4:5] op_sel_hi:[1,0]
	v_pk_mul_f32 v[14:15], v[14:15], v[4:5] op_sel_hi:[1,0]
	v_pk_fma_f32 v[18:19], v[96:97], v[8:9], v[112:113]
	s_nop 0
	v_cvt_pk_f16_f32 v5, v18, v19
	v_pk_fma_f32 v[14:15], v[98:99], v[14:15], v[114:115]
	v_add_u32_e32 v5, 0x20002, v5
	v_and_b32_e32 v20, 0xfffcfffc, v5
	v_cvt_pk_f16_f32 v5, v14, v15
	v_add_u32_e32 v5, 0x20002, v5
	v_and_b32_e32 v21, 0xfffcfffc, v5
	v_mov_b32_e32 v5, v33
	v_cvt_pk_fp8_f32 v5, v18, v19
	v_lshl_add_u64 v[8:9], v[68:69], 0, s[14:15]
	global_store_dwordx2 v[8:9], v[20:21], off
	v_cvt_pk_fp8_f32 v5, v14, v15 op_sel:[0,0,1]
	v_lshl_add_u64 v[14:15], v[72:73], 0, s[4:5]
	s_add_i32 s4, s87, s6
	s_add_u32 s8, s8, s68
	global_store_dword v[14:15], v5, off
	v_pk_mul_f32 v[16:17], v[16:17], v[4:5] op_sel_hi:[1,0]
	v_pk_mul_f32 v[10:11], v[10:11], v[4:5] op_sel_hi:[1,0]
	s_addc_u32 s9, s9, s69
	s_add_u32 s12, s12, s68
	s_addc_u32 s13, s13, s69
	s_cmpk_gt_i32 s4, 0x3fff
	v_pk_fma_f32 v[16:17], v[100:101], v[16:17], v[116:117]
	s_nop 0
	v_cvt_pk_f16_f32 v5, v16, v17
	v_pk_fma_f32 v[10:11], v[102:103], v[10:11], v[118:119]
	v_add_u32_e32 v5, 0x20002, v5
	v_and_b32_e32 v18, 0xfffcfffc, v5
	v_cvt_pk_f16_f32 v5, v10, v11
	v_add_u32_e32 v5, 0x20002, v5
	v_and_b32_e32 v19, 0xfffcfffc, v5
	v_mov_b32_e32 v5, v33
	v_cvt_pk_fp8_f32 v5, v16, v17
	global_store_dwordx2 v[8:9], v[18:19], off offset:512
	v_cvt_pk_fp8_f32 v5, v10, v11 op_sel:[0,0,1]
	global_store_dword v[14:15], v5, off offset:256
	v_pk_mul_f32 v[10:11], v[12:13], v[4:5] op_sel_hi:[1,0]
	v_pk_mul_f32 v[6:7], v[6:7], v[4:5] op_sel_hi:[1,0]
	v_pk_fma_f32 v[10:11], v[104:105], v[10:11], v[120:121]
	s_nop 0
	v_cvt_pk_f16_f32 v5, v10, v11
	v_pk_fma_f32 v[6:7], v[106:107], v[6:7], v[122:123]
	v_add_u32_e32 v5, 0x20002, v5
	v_and_b32_e32 v12, 0xfffcfffc, v5
	v_cvt_pk_f16_f32 v5, v6, v7
	v_add_u32_e32 v5, 0x20002, v5
	v_and_b32_e32 v13, 0xfffcfffc, v5
	v_mov_b32_e32 v5, v33
	v_cvt_pk_fp8_f32 v5, v10, v11
	global_store_dwordx2 v[8:9], v[12:13], off offset:1024
	v_cvt_pk_fp8_f32 v5, v6, v7 op_sel:[0,0,1]
	global_store_dword v[14:15], v5, off offset:512
	v_pk_mul_f32 v[0:1], v[0:1], v[4:5] op_sel_hi:[1,0]
	v_pk_mul_f32 v[2:3], v[2:3], v[4:5] op_sel_hi:[1,0]
	v_pk_fma_f32 v[0:1], v[0:1], v[108:109], v[124:125]
	v_pk_fma_f32 v[2:3], v[2:3], v[110:111], v[126:127]
	v_cvt_pk_f16_f32 v4, v0, v1
	v_cvt_pk_f16_f32 v5, v2, v3
	v_add_u32_e32 v4, 0x20002, v4
	v_add_u32_e32 v5, 0x20002, v5
	v_and_b32_e32 v4, 0xfffcfffc, v4
	v_and_b32_e32 v5, 0xfffcfffc, v5
	global_store_dwordx2 v[8:9], v[4:5], off offset:1536
	v_mov_b32_e32 v4, v33
	v_cvt_pk_fp8_f32 v4, v0, v1
	v_cvt_pk_fp8_f32 v4, v2, v3 op_sel:[0,0,1]
	global_store_dword v[14:15], v4, off offset:768
	s_cbranch_scc0 .LBB0_575
